# attention tile loop: the 8 steady-path v_mov_b64 between MFMAs split into v_mov_b32 pairs
# baseline (speedup 1.0000x reference)
.LBB0_423:
	v_add_u32_e32 v81, s5, v206
	ds_read_b128 v[82:85], v81
	ds_read_b128 v[86:89], v81 offset:4096
	v_add_u32_e32 v90, s5, v207
	v_add_u32_e32 v94, s5, v208
	v_exp_f32_e32 v128, v128
	v_exp_f32_e32 v129, v129
	v_exp_f32_e32 v152, v96
	v_exp_f32_e32 v153, v97
	v_add_u32_e32 v81, s5, v209
	s_waitcnt lgkmcnt(1)
	v_mfma_f32_32x32x16_bf16 v[112:127], v[82:85], v[160:163], v[64:79]
	ds_read_b128 v[82:85], v90
	ds_read_b128 v[90:93], v90 offset:4096
	ds_read_b128 v[144:147], v94
	ds_read_b128 v[148:151], v94 offset:4096
	v_add_f32_e32 v154, v153, v152
	v_exp_f32_e32 v108, v108
	v_exp_f32_e32 v109, v109
	v_exp_f32_e32 v110, v110
	v_exp_f32_e32 v111, v111
	s_add_i32 s4, s4, 2
	s_waitcnt lgkmcnt(4)
	v_mfma_f32_32x32x16_bf16 v[216:231], v[86:89], v[160:163], v[64:79]
	ds_read_b128 v[86:89], v81
	ds_read_b128 v[94:97], v81 offset:4096
	v_add_f32_e32 v81, v129, v128
	v_add_f32_e32 v81, v154, v81
	v_cvt_pk_bf16_f32 v128, v128, v129
	s_add_i32 s5, s76, s77
	s_cmpk_eq_i32 s5, 0x2000
	s_waitcnt lgkmcnt(5)
	v_mfma_f32_32x32x16_bf16 v[112:127], v[82:85], v[164:167], v[112:127]
	v_exp_f32_e32 v83, v130
	v_exp_f32_e32 v84, v131
	v_exp_f32_e32 v85, v98
	v_exp_f32_e32 v98, v99
	v_exp_f32_e32 v99, v103
	v_cvt_pk_bf16_f32 v129, v83, v84
	v_exp_f32_e32 v103, v137
	s_waitcnt lgkmcnt(4)
	v_mfma_f32_32x32x16_bf16 v[216:231], v[90:93], v[164:167], v[216:231]
	v_add_f32_e32 v90, v84, v83
	v_add_f32_e32 v91, v98, v85
	v_add_f32_e32 v90, v91, v90
	v_add_f32_e32 v81, v90, v81
	v_exp_f32_e32 v90, v132
	v_exp_f32_e32 v91, v133
	v_exp_f32_e32 v92, v100
	v_exp_f32_e32 v93, v101
	s_waitcnt lgkmcnt(3)
	v_mfma_f32_32x32x16_bf16 v[112:127], v[144:147], v[168:171], v[112:127]
	v_cvt_pk_bf16_f32 v83, v85, v98
	v_add_f32_e32 v84, v91, v90
	v_add_f32_e32 v85, v93, v92
	v_add_f32_e32 v84, v85, v84
	v_cvt_pk_bf16_f32 v130, v90, v91
	v_exp_f32_e32 v85, v134
	v_exp_f32_e32 v90, v135
	s_waitcnt lgkmcnt(2)
	v_mfma_f32_32x32x16_bf16 v[216:231], v[148:151], v[168:171], v[216:231]
	v_exp_f32_e32 v98, v102
	v_add_f32_e32 v81, v84, v81
	v_add_f32_e32 v91, v90, v85
	v_exp_f32_e32 v102, v136
	v_exp_f32_e32 v136, v104
	v_exp_f32_e32 v137, v105
	v_cvt_pk_bf16_f32 v84, v92, v93
	s_waitcnt lgkmcnt(1)
	v_mfma_f32_32x32x16_bf16 v[112:127], v[86:89], v[172:175], v[112:127]
	v_add_f32_e32 v86, v99, v98
	v_add_f32_e32 v86, v86, v91
	v_add_f32_e32 v81, v86, v81
	ds_read_b64_tr_b16 v[86:87], v213 offset:40960
	ds_read_b64_tr_b16 v[88:89], v213 offset:43008
	v_cvt_pk_bf16_f32 v131, v85, v90
	v_add_f32_e32 v104, v103, v102
	v_add_f32_e32 v105, v137, v136
	s_waitcnt lgkmcnt(2)
	v_mfma_f32_32x32x16_bf16 v[216:231], v[94:97], v[172:175], v[216:231]
	ds_read_b64_tr_b16 v[90:91], v214 offset:40960
	ds_read_b64_tr_b16 v[92:93], v214 offset:43008
	ds_read_b64_tr_b16 v[94:95], v213 offset:45056
	ds_read_b64_tr_b16 v[96:97], v213 offset:47104
	v_cvt_pk_bf16_f32 v85, v98, v99
	v_cvt_pk_bf16_f32 v82, v152, v153
	s_cselect_b32 s8, s71, 0x2000
	s_cmpk_lg_i32 s5, 0x6000
	s_cselect_b32 s77, s8, 0
	s_add_u32 s38, s38, 0x40000
	s_waitcnt lgkmcnt(2)
	v_mfma_f32_32x32x16_bf16 v[32:47], v[90:93], v[128:131], v[32:47]
	v_add_f32_e32 v90, v105, v104
	v_add_f32_e32 v81, v90, v81
	v_cvt_pk_bf16_f32 v90, v102, v103
	v_exp_f32_e32 v91, v138
	v_exp_f32_e32 v92, v139
	v_exp_f32_e32 v138, v106
	v_exp_f32_e32 v106, v140
	v_mfma_f32_32x32x16_bf16 v[48:63], v[86:89], v[128:131], v[48:63]
	ds_read_b64_tr_b16 v[86:87], v215 offset:40960
	ds_read_b64_tr_b16 v[88:89], v215 offset:43008
	ds_read_b64_tr_b16 v[98:99], v214 offset:45056
	ds_read_b64_tr_b16 v[100:101], v214 offset:47104
	ds_read_b64_tr_b16 v[102:103], v248 offset:40960
	ds_read_b64_tr_b16 v[104:105], v248 offset:43008
	ds_read_b64_tr_b16 v[132:133], v215 offset:45056
	ds_read_b64_tr_b16 v[134:135], v215 offset:47104
	v_exp_f32_e32 v139, v107
	v_mov_b32_e32 v158, v230
	v_mov_b32_e32 v159, v231
	s_addc_u32 s39, s39, 0
	s_add_i32 s75, s75, 0x20000
	s_and_b64 vcc, exec, s[6:7]
	s_waitcnt lgkmcnt(2)
	v_mfma_f32_32x32x16_bf16 v[0:15], v[102:105], v[128:131], v[0:15]
	v_exp_f32_e32 v102, v141
	v_exp_f32_e32 v103, v142
	v_exp_f32_e32 v104, v143
	v_add_f32_e32 v105, v92, v91
	v_cvt_pk_bf16_f32 v91, v91, v92
	v_cvt_pk_bf16_f32 v92, v106, v102
	v_cvt_pk_bf16_f32 v93, v103, v104
	v_mfma_f32_32x32x16_bf16 v[16:31], v[86:89], v[128:131], v[16:31]
	ds_read_b64_tr_b16 v[86:87], v248 offset:45056
	ds_read_b64_tr_b16 v[88:89], v248 offset:47104
	v_mov_b32_e32 v156, v228
	v_mov_b32_e32 v157, v229
	v_mov_b32_e32 v154, v226
	v_mov_b32_e32 v155, v227
	v_mov_b32_e32 v152, v224
	v_mov_b32_e32 v153, v225
	v_mov_b32_e32 v150, v222
	v_mov_b32_e32 v151, v223
	v_mov_b32_e32 v148, v220
	v_mov_b32_e32 v149, v221
	v_mov_b32_e32 v146, v218
	v_mov_b32_e32 v147, v219
	v_mfma_f32_32x32x16_bf16 v[48:63], v[94:97], v[90:93], v[48:63]
	v_add_f32_e32 v94, v139, v138
	v_add_f32_e32 v94, v94, v105
	v_add_f32_e32 v81, v94, v81
	v_add_f32_e32 v94, v102, v106
	v_add_f32_e32 v95, v109, v108
	v_add_f32_e32 v94, v95, v94
	v_add_f32_e32 v81, v94, v81
	v_mfma_f32_32x32x16_bf16 v[32:47], v[98:101], v[90:93], v[32:47]
	v_add_f32_e32 v94, v104, v103
	v_add_f32_e32 v95, v111, v110
	v_add_f32_e32 v94, v95, v94
	v_add_f32_e32 v106, v94, v81
	v_max_f32_e32 v81, v113, v113
	v_max_f32_e32 v94, v112, v112
	v_max_f32_e32 v81, v94, v81
	s_waitcnt lgkmcnt(2)
	v_mfma_f32_32x32x16_bf16 v[16:31], v[132:135], v[90:93], v[16:31]
	ds_read_b64_tr_b16 v[94:95], v213 offset:49152
	ds_read_b64_tr_b16 v[96:97], v213 offset:51200
	v_max3_f32 v81, v81, v114, v115
	v_max3_f32 v81, v81, v116, v117
	v_max3_f32 v81, v81, v118, v119
	v_max3_f32 v81, v81, v120, v121
	v_max3_f32 v81, v81, v122, v123
	v_max3_f32 v81, v81, v124, v125
	s_waitcnt lgkmcnt(2)
	v_mfma_f32_32x32x16_bf16 v[0:15], v[86:89], v[90:93], v[0:15]
	ds_read_b64_tr_b16 v[86:87], v214 offset:49152
	ds_read_b64_tr_b16 v[88:89], v214 offset:51200
	ds_read_b64_tr_b16 v[90:91], v213 offset:53248
	ds_read_b64_tr_b16 v[92:93], v213 offset:55296
	v_max3_f32 v81, v81, v126, v127
	v_max3_f32 v81, v81, v216, v217
	v_max3_f32 v81, v81, v218, v219
	v_max3_f32 v81, v81, v220, v221
	v_max3_f32 v81, v81, v222, v223
	v_max3_f32 v81, v81, v224, v225
	s_waitcnt lgkmcnt(4)
	v_mfma_f32_32x32x16_bf16 v[48:63], v[94:97], v[82:85], v[48:63]
	ds_read_b64_tr_b16 v[94:95], v215 offset:49152
	ds_read_b64_tr_b16 v[96:97], v215 offset:51200
	ds_read_b64_tr_b16 v[98:99], v214 offset:53248
	ds_read_b64_tr_b16 v[100:101], v214 offset:55296
	v_max3_f32 v81, v81, v226, v227
	v_max3_f32 v81, v81, v228, v229
	v_max3_f32 v107, v81, v230, v231
	v_add_f32_e32 v196, v194, v106
	v_add_f32_e32 v197, v195, v107
	v_mov_b32_e32 v144, v216
	v_mov_b32_e32 v145, v217
	s_waitcnt lgkmcnt(6)
	v_mfma_f32_32x32x16_bf16 v[32:47], v[86:89], v[82:85], v[32:47]
	ds_read_b64_tr_b16 v[86:87], v248 offset:49152
	ds_read_b64_tr_b16 v[88:89], v248 offset:51200
	ds_read_b64_tr_b16 v[102:103], v215 offset:53248
	ds_read_b64_tr_b16 v[104:105], v215 offset:55296
	s_waitcnt lgkmcnt(6)
	v_mfma_f32_32x32x16_bf16 v[16:31], v[94:97], v[82:85], v[16:31]
	ds_read_b64_tr_b16 v[94:95], v248 offset:53248
	ds_read_b64_tr_b16 v[96:97], v248 offset:55296
	s_waitcnt vmcnt(0)
	s_waitcnt lgkmcnt(4)
	v_mfma_f32_32x32x16_bf16 v[0:15], v[86:89], v[82:85], v[0:15]
	v_cvt_pk_bf16_f32 v85, v110, v111
	v_cvt_pk_bf16_f32 v84, v108, v109
	v_cvt_pk_bf16_f32 v83, v138, v139
	v_cvt_pk_bf16_f32 v82, v136, v137
	s_nop 1
	v_mfma_f32_32x32x16_bf16 v[48:63], v[90:93], v[82:85], v[48:63]
	s_waitcnt lgkmcnt(0)
	s_barrier
	v_mfma_f32_32x32x16_bf16 v[32:47], v[98:101], v[82:85], v[32:47]
	v_mfma_f32_32x32x16_bf16 v[16:31], v[102:105], v[82:85], v[16:31]
	v_mfma_f32_32x32x16_bf16 v[0:15], v[94:97], v[82:85], v[0:15]
	s_cbranch_vccnz .LBB0_432
